# fast f32 rcp division in all GEMM epilogues + attention (no RES change)
# speedup vs baseline: 1.0271x; 1.0030x over previous
.LBB0_480:
	v_ashrrev_i32_e32 v135, 31, v134
	v_lshl_add_u64 v[66:67], v[134:135], 2, s[8:9]
	global_load_dword v0, v[66:67], off
	v_cmp_lt_i32_e32 vcc, v196, v190
	v_lshlrev_b32_e32 v68, 2, v166
	v_lshl_add_u64 v[66:67], v[132:133], 1, s[6:7]
	s_add_i32 s16, s16, s70
	s_cmpk_gt_i32 s16, 0x1ff
	s_waitcnt vmcnt(0)
	v_mul_f32_e32 v0, 0x3fb8aa3b, v0
	v_exp_f32_e32 v69, v0
	v_cndmask_b32_e32 v0, v179, v196, vcc
	v_lshlrev_b32_e32 v70, 2, v0
	ds_bpermute_b32 v71, v70, v130
	v_lshlrev_b32_e32 v0, 1, v165
	v_lshl_add_u64 v[66:67], v[66:67], 0, v[0:1]
	v_or_b32_e32 v0, v189, v68
	v_lshlrev_b32_e32 v0, 2, v0
	s_waitcnt lgkmcnt(0)
	v_add_f32_e32 v71, v130, v71
	v_add_f32_e32 v71, v69, v71
	v_rcp_f32_e32 v73, v71
	s_nop 0
	v_mov_b32_e32 v71, v73
	ds_bpermute_b32 v74, v0, v71
	v_or_b32_e32 v72, v68, v164
	v_ashrrev_i32_e32 v73, 31, v72
	v_lshlrev_b64 v[72:73], 11, v[72:73]
	v_lshl_add_u64 v[72:73], v[66:67], 0, v[72:73]
	s_waitcnt lgkmcnt(0)
	v_mul_f32_e32 v34, v34, v74
	v_cvt_pk_bf16_f32 v34, v34, s0
	global_store_short v[72:73], v34, off
	v_mul_f32_e32 v34, v50, v74
	v_cvt_pk_bf16_f32 v34, v34, s0
	global_store_short v[72:73], v34, off offset:64
	v_or_b32_e32 v34, 1, v68
	v_or_b32_e32 v50, v189, v34
	v_lshlrev_b32_e32 v50, 2, v50
	ds_bpermute_b32 v74, v50, v71
	v_or_b32_e32 v72, v34, v164
	v_ashrrev_i32_e32 v73, 31, v72
	v_lshlrev_b64 v[72:73], 11, v[72:73]
	v_lshl_add_u64 v[72:73], v[66:67], 0, v[72:73]
	s_waitcnt lgkmcnt(0)
	v_mul_f32_e32 v35, v35, v74
	v_cvt_pk_bf16_f32 v35, v35, s0
	global_store_short v[72:73], v35, off
	v_mul_f32_e32 v35, v51, v74
	v_cvt_pk_bf16_f32 v35, v35, s0
	global_store_short v[72:73], v35, off offset:64
	v_or_b32_e32 v35, 2, v68
	v_or_b32_e32 v51, v189, v35
	v_lshlrev_b32_e32 v51, 2, v51
	ds_bpermute_b32 v74, v51, v71
	v_or_b32_e32 v72, v35, v164
	v_ashrrev_i32_e32 v73, 31, v72
	v_lshlrev_b64 v[72:73], 11, v[72:73]
	v_lshl_add_u64 v[72:73], v[66:67], 0, v[72:73]
	s_waitcnt lgkmcnt(0)
	v_mul_f32_e32 v36, v36, v74
	v_cvt_pk_bf16_f32 v36, v36, s0
	global_store_short v[72:73], v36, off
	v_mul_f32_e32 v36, v52, v74
	v_cvt_pk_bf16_f32 v36, v36, s0
	global_store_short v[72:73], v36, off offset:64
	v_or_b32_e32 v36, 3, v68
	v_or_b32_e32 v52, v189, v36
	v_lshlrev_b32_e32 v52, 2, v52
	ds_bpermute_b32 v74, v52, v71
	v_or_b32_e32 v72, v36, v164
	v_ashrrev_i32_e32 v73, 31, v72
	v_lshlrev_b64 v[72:73], 11, v[72:73]
	v_lshl_add_u64 v[72:73], v[66:67], 0, v[72:73]
	s_waitcnt lgkmcnt(0)
	v_mul_f32_e32 v37, v37, v74
	v_cvt_pk_bf16_f32 v37, v37, s0
	global_store_short v[72:73], v37, off
	v_mul_f32_e32 v37, v53, v74
	v_cvt_pk_bf16_f32 v37, v37, s0
	global_store_short v[72:73], v37, off offset:64
	v_or_b32_e32 v37, 8, v68
	v_or_b32_e32 v53, v189, v37
	v_lshlrev_b32_e32 v53, 2, v53
	ds_bpermute_b32 v74, v53, v71
	v_or_b32_e32 v72, v37, v164
	v_ashrrev_i32_e32 v73, 31, v72
	v_lshlrev_b64 v[72:73], 11, v[72:73]
	v_lshl_add_u64 v[72:73], v[66:67], 0, v[72:73]
	s_waitcnt lgkmcnt(0)
	v_mul_f32_e32 v38, v38, v74
	v_cvt_pk_bf16_f32 v38, v38, s0
	global_store_short v[72:73], v38, off
	v_mul_f32_e32 v38, v54, v74
	v_cvt_pk_bf16_f32 v38, v38, s0
	global_store_short v[72:73], v38, off offset:64
	v_or_b32_e32 v38, 9, v68
	v_or_b32_e32 v54, v189, v38
	v_lshlrev_b32_e32 v54, 2, v54
	ds_bpermute_b32 v74, v54, v71
	v_or_b32_e32 v72, v38, v164
	v_ashrrev_i32_e32 v73, 31, v72
	v_lshlrev_b64 v[72:73], 11, v[72:73]
	v_lshl_add_u64 v[72:73], v[66:67], 0, v[72:73]
	s_waitcnt lgkmcnt(0)
	v_mul_f32_e32 v39, v39, v74
	v_cvt_pk_bf16_f32 v39, v39, s0
	global_store_short v[72:73], v39, off
	v_mul_f32_e32 v39, v55, v74
	v_cvt_pk_bf16_f32 v39, v39, s0
	global_store_short v[72:73], v39, off offset:64
	v_or_b32_e32 v39, 10, v68
	v_or_b32_e32 v55, v189, v39
	v_lshlrev_b32_e32 v55, 2, v55
	ds_bpermute_b32 v74, v55, v71
	v_or_b32_e32 v72, v39, v164
	v_ashrrev_i32_e32 v73, 31, v72
	v_lshlrev_b64 v[72:73], 11, v[72:73]
	v_lshl_add_u64 v[72:73], v[66:67], 0, v[72:73]
	s_waitcnt lgkmcnt(0)
	v_mul_f32_e32 v40, v40, v74
	v_cvt_pk_bf16_f32 v40, v40, s0
	global_store_short v[72:73], v40, off
	v_mul_f32_e32 v40, v56, v74
	v_cvt_pk_bf16_f32 v40, v40, s0
	v_or_b32_e32 v56, 11, v68
	global_store_short v[72:73], v40, off offset:64
	v_or_b32_e32 v40, v189, v56
	v_lshlrev_b32_e32 v74, 2, v40
	ds_bpermute_b32 v40, v74, v71
	v_or_b32_e32 v72, v56, v164
	v_ashrrev_i32_e32 v73, 31, v72
	v_lshlrev_b64 v[72:73], 11, v[72:73]
	v_lshl_add_u64 v[72:73], v[66:67], 0, v[72:73]
	s_waitcnt lgkmcnt(0)
	v_mul_f32_e32 v41, v41, v40
	v_mul_f32_e32 v40, v57, v40
	v_cvt_pk_bf16_f32 v40, v40, s0
	v_or_b32_e32 v57, 16, v68
	v_cvt_pk_bf16_f32 v41, v41, s0
	global_store_short v[72:73], v40, off offset:64
	v_or_b32_e32 v40, v189, v57
	global_store_short v[72:73], v41, off
	v_lshlrev_b32_e32 v72, 2, v40
	ds_bpermute_b32 v73, v72, v71
	v_or_b32_e32 v40, v57, v164
	v_ashrrev_i32_e32 v41, 31, v40
	v_lshlrev_b64 v[40:41], 11, v[40:41]
	v_lshl_add_u64 v[40:41], v[66:67], 0, v[40:41]
	s_waitcnt lgkmcnt(0)
	v_mul_f32_e32 v42, v42, v73
	v_cvt_pk_bf16_f32 v42, v42, s0
	global_store_short v[40:41], v42, off
	v_mul_f32_e32 v42, v58, v73
	v_cvt_pk_bf16_f32 v42, v42, s0
	global_store_short v[40:41], v42, off offset:64
	v_or_b32_e32 v42, 17, v68
	v_or_b32_e32 v40, v189, v42
	v_lshlrev_b32_e32 v58, 2, v40
	ds_bpermute_b32 v73, v58, v71
	v_or_b32_e32 v40, v42, v164
	v_ashrrev_i32_e32 v41, 31, v40
	v_lshlrev_b64 v[40:41], 11, v[40:41]
	v_lshl_add_u64 v[40:41], v[66:67], 0, v[40:41]
	s_waitcnt lgkmcnt(0)
	v_mul_f32_e32 v43, v43, v73
	v_cvt_pk_bf16_f32 v43, v43, s0
	global_store_short v[40:41], v43, off
	v_mul_f32_e32 v43, v59, v73
	v_cvt_pk_bf16_f32 v43, v43, s0
	global_store_short v[40:41], v43, off offset:64
	v_or_b32_e32 v43, 18, v68
	v_or_b32_e32 v40, v189, v43
	v_lshlrev_b32_e32 v59, 2, v40
	ds_bpermute_b32 v73, v59, v71
	v_or_b32_e32 v40, v43, v164
	v_ashrrev_i32_e32 v41, 31, v40
	v_lshlrev_b64 v[40:41], 11, v[40:41]
	v_lshl_add_u64 v[40:41], v[66:67], 0, v[40:41]
	s_waitcnt lgkmcnt(0)
	v_mul_f32_e32 v44, v44, v73
	v_cvt_pk_bf16_f32 v44, v44, s0
	global_store_short v[40:41], v44, off
	v_mul_f32_e32 v44, v60, v73
	v_cvt_pk_bf16_f32 v44, v44, s0
	global_store_short v[40:41], v44, off offset:64
	v_or_b32_e32 v44, 19, v68
	v_or_b32_e32 v40, v189, v44
	v_lshlrev_b32_e32 v60, 2, v40
	ds_bpermute_b32 v73, v60, v71
	v_or_b32_e32 v40, v44, v164
	v_ashrrev_i32_e32 v41, 31, v40
	v_lshlrev_b64 v[40:41], 11, v[40:41]
	v_lshl_add_u64 v[40:41], v[66:67], 0, v[40:41]
	s_waitcnt lgkmcnt(0)
	v_mul_f32_e32 v45, v45, v73
	v_cvt_pk_bf16_f32 v45, v45, s0
	global_store_short v[40:41], v45, off
	v_mul_f32_e32 v45, v61, v73
	v_cvt_pk_bf16_f32 v45, v45, s0
	global_store_short v[40:41], v45, off offset:64
	v_or_b32_e32 v45, 24, v68
	v_or_b32_e32 v40, v189, v45
	v_lshlrev_b32_e32 v61, 2, v40
	ds_bpermute_b32 v73, v61, v71
	v_or_b32_e32 v40, v45, v164
	v_ashrrev_i32_e32 v41, 31, v40
	v_lshlrev_b64 v[40:41], 11, v[40:41]
	v_lshl_add_u64 v[40:41], v[66:67], 0, v[40:41]
	s_waitcnt lgkmcnt(0)
	v_mul_f32_e32 v46, v46, v73
	v_cvt_pk_bf16_f32 v46, v46, s0
	global_store_short v[40:41], v46, off
	v_mul_f32_e32 v46, v62, v73
	v_cvt_pk_bf16_f32 v46, v46, s0
	global_store_short v[40:41], v46, off offset:64
	v_or_b32_e32 v46, 25, v68
	v_or_b32_e32 v40, v189, v46
	v_lshlrev_b32_e32 v62, 2, v40
	ds_bpermute_b32 v73, v62, v71
	v_or_b32_e32 v40, v46, v164
	v_ashrrev_i32_e32 v41, 31, v40
	v_lshlrev_b64 v[40:41], 11, v[40:41]
	v_lshl_add_u64 v[40:41], v[66:67], 0, v[40:41]
	s_waitcnt lgkmcnt(0)
	v_mul_f32_e32 v47, v47, v73
	v_cvt_pk_bf16_f32 v47, v47, s0
	global_store_short v[40:41], v47, off
	v_mul_f32_e32 v47, v63, v73
	v_cvt_pk_bf16_f32 v47, v47, s0
	global_store_short v[40:41], v47, off offset:64
	v_or_b32_e32 v47, 26, v68
	v_or_b32_e32 v40, v189, v47
	v_lshlrev_b32_e32 v63, 2, v40
	ds_bpermute_b32 v73, v63, v71
	v_or_b32_e32 v40, v47, v164
	v_ashrrev_i32_e32 v41, 31, v40
	v_lshlrev_b64 v[40:41], 11, v[40:41]
	v_lshl_add_u64 v[40:41], v[66:67], 0, v[40:41]
	s_waitcnt lgkmcnt(0)
	v_mul_f32_e32 v48, v48, v73
	v_cvt_pk_bf16_f32 v48, v48, s0
	global_store_short v[40:41], v48, off
	v_mul_f32_e32 v48, v64, v73
	v_cvt_pk_bf16_f32 v48, v48, s0
	global_store_short v[40:41], v48, off offset:64
	v_or_b32_e32 v48, 27, v68
	v_or_b32_e32 v40, v189, v48
	v_lshlrev_b32_e32 v64, 2, v40
	ds_bpermute_b32 v71, v64, v71
	v_or_b32_e32 v40, v48, v164
	v_ashrrev_i32_e32 v41, 31, v40
	v_lshlrev_b64 v[40:41], 11, v[40:41]
	v_lshl_add_u64 v[40:41], v[66:67], 0, v[40:41]
	s_waitcnt lgkmcnt(0)
	v_mul_f32_e32 v49, v49, v71
	v_cvt_pk_bf16_f32 v49, v49, s0
	global_store_short v[40:41], v49, off
	v_mul_f32_e32 v49, v65, v71
	v_cvt_pk_bf16_f32 v49, v49, s0
	global_store_short v[40:41], v49, off offset:64
	ds_bpermute_b32 v40, v70, v131
	s_waitcnt lgkmcnt(0)
	v_add_f32_e32 v40, v131, v40
	v_add_f32_e32 v40, v69, v40
	v_rcp_f32_e32 v49, v40
	s_nop 0
	v_mov_b32_e32 v49, v49
	ds_bpermute_b32 v0, v0, v49
	v_or_b32_e32 v65, 32, v164
	v_or_b32_e32 v40, v68, v65
	v_ashrrev_i32_e32 v41, 31, v40
	v_lshlrev_b64 v[40:41], 11, v[40:41]
	s_waitcnt lgkmcnt(0)
	v_mul_f32_e32 v18, v18, v0
	v_mul_f32_e32 v0, v2, v0
	v_lshl_add_u64 v[40:41], v[66:67], 0, v[40:41]
	v_cvt_pk_bf16_f32 v0, v0, s0
	global_store_short v[40:41], v0, off offset:64
	ds_bpermute_b32 v0, v50, v49
	v_cvt_pk_bf16_f32 v18, v18, s0
	global_store_short v[40:41], v18, off
	v_or_b32_e32 v40, v34, v65
	v_ashrrev_i32_e32 v41, 31, v40
	v_lshlrev_b64 v[40:41], 11, v[40:41]
	s_waitcnt lgkmcnt(0)
	v_mul_f32_e32 v2, v19, v0
	v_mul_f32_e32 v0, v3, v0
	v_lshl_add_u64 v[40:41], v[66:67], 0, v[40:41]
	v_cvt_pk_bf16_f32 v0, v0, s0
	global_store_short v[40:41], v0, off offset:64
	ds_bpermute_b32 v0, v51, v49
	v_cvt_pk_bf16_f32 v2, v2, s0
	global_store_short v[40:41], v2, off
	v_or_b32_e32 v2, v35, v65
	v_ashrrev_i32_e32 v3, 31, v2
	v_lshlrev_b64 v[2:3], 11, v[2:3]
	s_waitcnt lgkmcnt(0)
	v_mul_f32_e32 v18, v20, v0
	v_mul_f32_e32 v0, v4, v0
	v_lshl_add_u64 v[2:3], v[66:67], 0, v[2:3]
	v_cvt_pk_bf16_f32 v0, v0, s0
	global_store_short v[2:3], v0, off offset:64
	ds_bpermute_b32 v0, v52, v49
	v_cvt_pk_bf16_f32 v18, v18, s0
	global_store_short v[2:3], v18, off
	v_or_b32_e32 v2, v36, v65
	v_ashrrev_i32_e32 v3, 31, v2
	v_lshlrev_b64 v[2:3], 11, v[2:3]
	s_waitcnt lgkmcnt(0)
	v_mul_f32_e32 v4, v21, v0
	v_mul_f32_e32 v0, v5, v0
	v_lshl_add_u64 v[2:3], v[66:67], 0, v[2:3]
	v_cvt_pk_bf16_f32 v0, v0, s0
	global_store_short v[2:3], v0, off offset:64
	ds_bpermute_b32 v0, v53, v49
	v_cvt_pk_bf16_f32 v4, v4, s0
	global_store_short v[2:3], v4, off
	v_or_b32_e32 v2, v37, v65
	v_ashrrev_i32_e32 v3, 31, v2
	v_lshlrev_b64 v[2:3], 11, v[2:3]
	s_waitcnt lgkmcnt(0)
	v_mul_f32_e32 v4, v22, v0
	v_mul_f32_e32 v0, v6, v0
	v_lshl_add_u64 v[2:3], v[66:67], 0, v[2:3]
	v_cvt_pk_bf16_f32 v0, v0, s0
	global_store_short v[2:3], v0, off offset:64
	ds_bpermute_b32 v0, v54, v49
	v_cvt_pk_bf16_f32 v4, v4, s0
	global_store_short v[2:3], v4, off
	v_or_b32_e32 v2, v38, v65
	v_ashrrev_i32_e32 v3, 31, v2
	v_lshlrev_b64 v[2:3], 11, v[2:3]
	s_waitcnt lgkmcnt(0)
	v_mul_f32_e32 v4, v23, v0
	v_mul_f32_e32 v0, v7, v0
	v_lshl_add_u64 v[2:3], v[66:67], 0, v[2:3]
	v_cvt_pk_bf16_f32 v0, v0, s0
	global_store_short v[2:3], v0, off offset:64
	ds_bpermute_b32 v0, v55, v49
	v_cvt_pk_bf16_f32 v4, v4, s0
	global_store_short v[2:3], v4, off
	v_or_b32_e32 v2, v39, v65
	v_ashrrev_i32_e32 v3, 31, v2
	v_lshlrev_b64 v[2:3], 11, v[2:3]
	s_waitcnt lgkmcnt(0)
	v_mul_f32_e32 v4, v24, v0
	v_mul_f32_e32 v0, v8, v0
	v_lshl_add_u64 v[2:3], v[66:67], 0, v[2:3]
	v_cvt_pk_bf16_f32 v0, v0, s0
	global_store_short v[2:3], v0, off offset:64
	ds_bpermute_b32 v0, v74, v49
	v_cvt_pk_bf16_f32 v4, v4, s0
	global_store_short v[2:3], v4, off
	v_or_b32_e32 v2, v56, v65
	v_ashrrev_i32_e32 v3, 31, v2
	v_lshlrev_b64 v[2:3], 11, v[2:3]
	s_waitcnt lgkmcnt(0)
	v_mul_f32_e32 v4, v25, v0
	v_mul_f32_e32 v0, v9, v0
	v_lshl_add_u64 v[2:3], v[66:67], 0, v[2:3]
	v_cvt_pk_bf16_f32 v0, v0, s0
	global_store_short v[2:3], v0, off offset:64
	ds_bpermute_b32 v0, v72, v49
	v_cvt_pk_bf16_f32 v4, v4, s0
	global_store_short v[2:3], v4, off
	v_or_b32_e32 v2, v57, v65
	v_ashrrev_i32_e32 v3, 31, v2
	v_lshlrev_b64 v[2:3], 11, v[2:3]
	s_waitcnt lgkmcnt(0)
	v_mul_f32_e32 v4, v26, v0
	v_mul_f32_e32 v0, v10, v0
	v_lshl_add_u64 v[2:3], v[66:67], 0, v[2:3]
	v_cvt_pk_bf16_f32 v0, v0, s0
	global_store_short v[2:3], v0, off offset:64
	ds_bpermute_b32 v0, v58, v49
	v_cvt_pk_bf16_f32 v4, v4, s0
	global_store_short v[2:3], v4, off
	v_or_b32_e32 v2, v42, v65
	v_ashrrev_i32_e32 v3, 31, v2
	v_lshlrev_b64 v[2:3], 11, v[2:3]
	s_waitcnt lgkmcnt(0)
	v_mul_f32_e32 v4, v27, v0
	v_mul_f32_e32 v0, v11, v0
	v_lshl_add_u64 v[2:3], v[66:67], 0, v[2:3]
	v_cvt_pk_bf16_f32 v0, v0, s0
	global_store_short v[2:3], v0, off offset:64
	ds_bpermute_b32 v0, v59, v49
	v_cvt_pk_bf16_f32 v4, v4, s0
	global_store_short v[2:3], v4, off
	v_or_b32_e32 v2, v43, v65
	v_ashrrev_i32_e32 v3, 31, v2
	v_lshlrev_b64 v[2:3], 11, v[2:3]
	s_waitcnt lgkmcnt(0)
	v_mul_f32_e32 v4, v28, v0
	v_mul_f32_e32 v0, v12, v0
	v_lshl_add_u64 v[2:3], v[66:67], 0, v[2:3]
	v_cvt_pk_bf16_f32 v0, v0, s0
	global_store_short v[2:3], v0, off offset:64
	ds_bpermute_b32 v0, v60, v49
	v_cvt_pk_bf16_f32 v4, v4, s0
	global_store_short v[2:3], v4, off
	v_or_b32_e32 v2, v44, v65
	v_ashrrev_i32_e32 v3, 31, v2
	v_lshlrev_b64 v[2:3], 11, v[2:3]
	s_waitcnt lgkmcnt(0)
	v_mul_f32_e32 v4, v29, v0
	v_mul_f32_e32 v0, v13, v0
	v_lshl_add_u64 v[2:3], v[66:67], 0, v[2:3]
	v_cvt_pk_bf16_f32 v0, v0, s0
	global_store_short v[2:3], v0, off offset:64
	ds_bpermute_b32 v0, v61, v49
	v_cvt_pk_bf16_f32 v4, v4, s0
	global_store_short v[2:3], v4, off
	v_or_b32_e32 v2, v45, v65
	v_ashrrev_i32_e32 v3, 31, v2
	v_lshlrev_b64 v[2:3], 11, v[2:3]
	s_waitcnt lgkmcnt(0)
	v_mul_f32_e32 v4, v30, v0
	v_mul_f32_e32 v0, v14, v0
	v_lshl_add_u64 v[2:3], v[66:67], 0, v[2:3]
	v_cvt_pk_bf16_f32 v0, v0, s0
	global_store_short v[2:3], v0, off offset:64
	ds_bpermute_b32 v0, v62, v49
	v_cvt_pk_bf16_f32 v4, v4, s0
	global_store_short v[2:3], v4, off
	v_or_b32_e32 v2, v46, v65
	v_ashrrev_i32_e32 v3, 31, v2
	v_lshlrev_b64 v[2:3], 11, v[2:3]
	s_waitcnt lgkmcnt(0)
	v_mul_f32_e32 v4, v31, v0
	v_mul_f32_e32 v0, v15, v0
	v_lshl_add_u64 v[2:3], v[66:67], 0, v[2:3]
	v_cvt_pk_bf16_f32 v0, v0, s0
	global_store_short v[2:3], v0, off offset:64
	ds_bpermute_b32 v0, v63, v49
	v_cvt_pk_bf16_f32 v4, v4, s0
	global_store_short v[2:3], v4, off
	v_or_b32_e32 v2, v47, v65
	v_ashrrev_i32_e32 v3, 31, v2
	v_lshlrev_b64 v[2:3], 11, v[2:3]
	s_waitcnt lgkmcnt(0)
	v_mul_f32_e32 v4, v32, v0
	v_mul_f32_e32 v0, v16, v0
	v_lshl_add_u64 v[2:3], v[66:67], 0, v[2:3]
	v_cvt_pk_bf16_f32 v0, v0, s0
	global_store_short v[2:3], v0, off offset:64
	ds_bpermute_b32 v0, v64, v49
	v_cvt_pk_bf16_f32 v4, v4, s0
	global_store_short v[2:3], v4, off
	v_or_b32_e32 v2, v48, v65
	v_ashrrev_i32_e32 v3, 31, v2
	v_lshlrev_b64 v[2:3], 11, v[2:3]
	s_waitcnt lgkmcnt(0)
	v_mul_f32_e32 v4, v33, v0
	v_mul_f32_e32 v0, v17, v0
	v_lshl_add_u64 v[2:3], v[66:67], 0, v[2:3]
	v_cvt_pk_bf16_f32 v4, v4, s0
	v_cvt_pk_bf16_f32 v0, v0, s0
	global_store_short v[2:3], v4, off
	global_store_short v[2:3], v0, off offset:64
	s_cbranch_scc1 .LBB0_496

.LBB0_899:
	s_and_b64 vcc, exec, s[2:3]
	s_cbranch_vccz .LBB0_901
	v_readlane_b32 s2, v253, 36
	v_add_u32_e32 v132, 0xfffffc00, v162
	v_ashrrev_i32_e32 v133, 31, v132
	v_mov_b32_e32 v0, s2
	ds_read_b64 v[130:131], v0
	v_ashrrev_i32_e32 v161, 31, v160
	v_mul_f32_e32 v0, 0xbfb8aa3b, v126
	s_waitcnt lgkmcnt(0)
	v_lshl_add_u64 v[130:131], v[132:133], 1, v[130:131]
	v_lshlrev_b64 v[132:133], 12, v[160:161]
	v_lshl_add_u64 v[130:131], v[130:131], 0, v[132:133]
	v_exp_f32_e32 v132, v0
	v_mul_f32_e32 v0, 0xbfb8aa3b, v127
	v_exp_f32_e32 v133, v0
	s_nop 0
	v_pk_add_f32 v[132:133], v[132:133], 1.0 op_sel_hi:[1,0]
	s_nop 0
	v_rcp_f32_e32 v134, v133
	s_nop 0
	v_mul_f32_e32 v0, v127, v134
	v_rcp_f32_e32 v134, v132
	s_nop 0
	v_mul_f32_e32 v134, v126, v134
	v_mul_f32_e32 v132, 0xbfb8aa3b, v128
	v_mul_f32_e32 v133, 0xbfb8aa3b, v129
	v_exp_f32_e32 v132, v132
	v_exp_f32_e32 v133, v133
	s_nop 0
	v_pk_add_f32 v[132:133], v[132:133], 1.0 op_sel_hi:[1,0]
	s_nop 0
	v_rcp_f32_e32 v136, v133
	s_nop 0
	v_mul_f32_e32 v133, v129, v136
	v_rcp_f32_e32 v136, v132
	s_nop 0
	v_mul_f32_e32 v135, v128, v136
	v_cvt_pk_bf16_f32 v132, v134, v0
	v_cvt_pk_bf16_f32 v133, v135, v133
	v_mul_f32_e32 v0, 0xbfb8aa3b, v118
	global_store_dwordx2 v[130:131], v[132:133], off
	v_exp_f32_e32 v132, v0
	v_mul_f32_e32 v0, 0xbfb8aa3b, v119
	v_exp_f32_e32 v133, v0
	s_nop 0
	v_pk_add_f32 v[132:133], v[132:133], 1.0 op_sel_hi:[1,0]
	s_nop 0
	v_rcp_f32_e32 v134, v133
	s_nop 0
	v_mul_f32_e32 v0, v119, v134
	v_rcp_f32_e32 v134, v132
	s_nop 0
	v_mul_f32_e32 v134, v118, v134
	v_mul_f32_e32 v132, 0xbfb8aa3b, v120
	v_mul_f32_e32 v133, 0xbfb8aa3b, v121
	v_exp_f32_e32 v132, v132
	v_exp_f32_e32 v133, v133
	s_nop 0
	v_pk_add_f32 v[132:133], v[132:133], 1.0 op_sel_hi:[1,0]
	s_nop 0
	v_rcp_f32_e32 v136, v133
	s_nop 0
	v_mul_f32_e32 v133, v121, v136
	v_rcp_f32_e32 v136, v132
	s_nop 0
	v_mul_f32_e32 v135, v120, v136
	v_cvt_pk_bf16_f32 v132, v134, v0
	v_cvt_pk_bf16_f32 v133, v135, v133
	v_mul_f32_e32 v0, 0xbfb8aa3b, v122
	global_store_dwordx2 v[130:131], v[132:133], off offset:32
	v_exp_f32_e32 v132, v0
	v_mul_f32_e32 v0, 0xbfb8aa3b, v123
	v_exp_f32_e32 v133, v0
	s_nop 0
	v_pk_add_f32 v[132:133], v[132:133], 1.0 op_sel_hi:[1,0]
	s_nop 0
	v_rcp_f32_e32 v134, v133
	s_nop 0
	v_mul_f32_e32 v0, v123, v134
	v_rcp_f32_e32 v134, v132
	s_nop 0
	v_mul_f32_e32 v134, v122, v134
	v_mul_f32_e32 v132, 0xbfb8aa3b, v124
	v_mul_f32_e32 v133, 0xbfb8aa3b, v125
	v_exp_f32_e32 v132, v132
	v_exp_f32_e32 v133, v133
	s_nop 0
	v_pk_add_f32 v[132:133], v[132:133], 1.0 op_sel_hi:[1,0]
	s_nop 0
	v_rcp_f32_e32 v136, v133
	s_nop 0
	v_mul_f32_e32 v133, v125, v136
	v_rcp_f32_e32 v136, v132
	s_nop 0
	v_mul_f32_e32 v135, v124, v136
	v_cvt_pk_bf16_f32 v132, v134, v0
	v_cvt_pk_bf16_f32 v133, v135, v133
	v_mul_f32_e32 v0, 0xbfb8aa3b, v114
	global_store_dwordx2 v[130:131], v[132:133], off offset:256
	v_exp_f32_e32 v132, v0
	v_mul_f32_e32 v0, 0xbfb8aa3b, v115
	v_exp_f32_e32 v133, v0
	s_nop 0
	v_pk_add_f32 v[132:133], v[132:133], 1.0 op_sel_hi:[1,0]
	s_nop 0
	v_rcp_f32_e32 v134, v133
	s_nop 0
	v_mul_f32_e32 v0, v115, v134
	v_rcp_f32_e32 v134, v132
	s_nop 0
	v_mul_f32_e32 v134, v114, v134
	v_mul_f32_e32 v132, 0xbfb8aa3b, v116
	v_mul_f32_e32 v133, 0xbfb8aa3b, v117
	v_exp_f32_e32 v132, v132
	v_exp_f32_e32 v133, v133
	s_nop 0
	v_pk_add_f32 v[132:133], v[132:133], 1.0 op_sel_hi:[1,0]
	s_nop 0
	v_rcp_f32_e32 v136, v133
	s_nop 0
	v_mul_f32_e32 v133, v117, v136
	v_rcp_f32_e32 v136, v132
	s_mov_b64 s[2:3], 0x10000
	v_mul_f32_e32 v135, v116, v136
	v_cvt_pk_bf16_f32 v132, v134, v0
	v_mul_f32_e32 v0, 0xbfb8aa3b, v110
	v_exp_f32_e32 v134, v0
	v_mul_f32_e32 v0, 0xbfb8aa3b, v111
	v_cvt_pk_bf16_f32 v133, v135, v133
	v_exp_f32_e32 v135, v0
	global_store_dwordx2 v[130:131], v[132:133], off offset:288
	v_lshl_add_u64 v[132:133], v[130:131], 0, s[2:3]
	v_pk_add_f32 v[134:135], v[134:135], 1.0 op_sel_hi:[1,0]
	s_nop 0
	v_rcp_f32_e32 v136, v135
	s_nop 0
	v_mul_f32_e32 v0, v111, v136
	v_rcp_f32_e32 v136, v134
	s_nop 0
	v_mul_f32_e32 v136, v110, v136
	v_mul_f32_e32 v134, 0xbfb8aa3b, v112
	v_mul_f32_e32 v135, 0xbfb8aa3b, v113
	v_exp_f32_e32 v134, v134
	v_exp_f32_e32 v135, v135
	s_nop 0
	v_pk_add_f32 v[134:135], v[134:135], 1.0 op_sel_hi:[1,0]
	s_nop 0
	v_rcp_f32_e32 v138, v135
	s_nop 0
	v_mul_f32_e32 v135, v113, v138
	v_rcp_f32_e32 v138, v134
	s_mov_b32 s2, 0x10000
	v_mul_f32_e32 v137, v112, v138
	v_cvt_pk_bf16_f32 v134, v136, v0
	v_add_co_u32_e32 v136, vcc, s2, v130
	v_cvt_pk_bf16_f32 v135, v137, v135
	s_nop 0
	v_addc_co_u32_e32 v137, vcc, 0, v131, vcc
	v_mul_f32_e32 v0, 0xbfb8aa3b, v102
	global_store_dwordx2 v[136:137], v[134:135], off
	v_exp_f32_e32 v134, v0
	v_mul_f32_e32 v0, 0xbfb8aa3b, v103
	v_exp_f32_e32 v135, v0
	s_nop 0
	v_pk_add_f32 v[134:135], v[134:135], 1.0 op_sel_hi:[1,0]
	s_nop 0
	v_rcp_f32_e32 v136, v135
	s_nop 0
	v_mul_f32_e32 v0, v103, v136
	v_rcp_f32_e32 v136, v134
	s_nop 0
	v_mul_f32_e32 v136, v102, v136
	v_mul_f32_e32 v134, 0xbfb8aa3b, v104
	v_mul_f32_e32 v135, 0xbfb8aa3b, v105
	v_exp_f32_e32 v134, v134
	v_exp_f32_e32 v135, v135
	s_nop 0
	v_pk_add_f32 v[134:135], v[134:135], 1.0 op_sel_hi:[1,0]
	s_nop 0
	v_rcp_f32_e32 v138, v135
	s_nop 0
	v_mul_f32_e32 v135, v105, v138
	v_rcp_f32_e32 v138, v134
	s_nop 0
	v_mul_f32_e32 v137, v104, v138
	v_cvt_pk_bf16_f32 v134, v136, v0
	v_cvt_pk_bf16_f32 v135, v137, v135
	v_mul_f32_e32 v0, 0xbfb8aa3b, v106
	global_store_dwordx2 v[132:133], v[134:135], off offset:32
	v_exp_f32_e32 v134, v0
	v_mul_f32_e32 v0, 0xbfb8aa3b, v107
	v_exp_f32_e32 v135, v0
	s_nop 0
	v_pk_add_f32 v[134:135], v[134:135], 1.0 op_sel_hi:[1,0]
	s_nop 0
	v_rcp_f32_e32 v136, v135
	s_nop 0
	v_mul_f32_e32 v0, v107, v136
	v_rcp_f32_e32 v136, v134
	s_nop 0
	v_mul_f32_e32 v136, v106, v136
	v_mul_f32_e32 v134, 0xbfb8aa3b, v108
	v_mul_f32_e32 v135, 0xbfb8aa3b, v109
	v_exp_f32_e32 v134, v134
	v_exp_f32_e32 v135, v135
	s_nop 0
	v_pk_add_f32 v[134:135], v[134:135], 1.0 op_sel_hi:[1,0]
	s_nop 0
	v_rcp_f32_e32 v138, v135
	s_nop 0
	v_mul_f32_e32 v135, v109, v138
	v_rcp_f32_e32 v138, v134
	s_nop 0
	v_mul_f32_e32 v137, v108, v138
	v_cvt_pk_bf16_f32 v134, v136, v0
	v_cvt_pk_bf16_f32 v135, v137, v135
	v_mul_f32_e32 v0, 0xbfb8aa3b, v98
	global_store_dwordx2 v[132:133], v[134:135], off offset:256
	v_exp_f32_e32 v134, v0
	v_mul_f32_e32 v0, 0xbfb8aa3b, v99
	v_exp_f32_e32 v135, v0
	s_nop 0
	v_pk_add_f32 v[134:135], v[134:135], 1.0 op_sel_hi:[1,0]
	s_nop 0
	v_rcp_f32_e32 v136, v135
	s_nop 0
	v_mul_f32_e32 v0, v99, v136
	v_rcp_f32_e32 v136, v134
	s_nop 0
	v_mul_f32_e32 v136, v98, v136
	v_mul_f32_e32 v134, 0xbfb8aa3b, v100
	v_mul_f32_e32 v135, 0xbfb8aa3b, v101
	v_exp_f32_e32 v134, v134
	v_exp_f32_e32 v135, v135
	s_nop 0
	v_pk_add_f32 v[134:135], v[134:135], 1.0 op_sel_hi:[1,0]
	s_nop 0
	v_rcp_f32_e32 v138, v135
	s_nop 0
	v_mul_f32_e32 v135, v101, v138
	v_rcp_f32_e32 v138, v134
	s_mov_b64 s[2:3], 0x20000
	v_mul_f32_e32 v137, v100, v138
	v_cvt_pk_bf16_f32 v134, v136, v0
	v_cvt_pk_bf16_f32 v135, v137, v135
	v_mul_f32_e32 v0, 0xbfb8aa3b, v94
	global_store_dwordx2 v[132:133], v[134:135], off offset:288
	v_exp_f32_e32 v134, v0
	v_mul_f32_e32 v0, 0xbfb8aa3b, v95
	v_exp_f32_e32 v135, v0
	v_lshl_add_u64 v[132:133], v[130:131], 0, s[2:3]
	v_pk_add_f32 v[134:135], v[134:135], 1.0 op_sel_hi:[1,0]
	s_nop 0
	v_rcp_f32_e32 v136, v135
	s_nop 0
	v_mul_f32_e32 v0, v95, v136
	v_rcp_f32_e32 v136, v134
	s_nop 0
	v_mul_f32_e32 v136, v94, v136
	v_mul_f32_e32 v134, 0xbfb8aa3b, v96
	v_mul_f32_e32 v135, 0xbfb8aa3b, v97
	v_exp_f32_e32 v134, v134
	v_exp_f32_e32 v135, v135
	s_nop 0
	v_pk_add_f32 v[134:135], v[134:135], 1.0 op_sel_hi:[1,0]
	s_nop 0
	v_rcp_f32_e32 v138, v135
	s_nop 0
	v_mul_f32_e32 v135, v97, v138
	v_rcp_f32_e32 v138, v134
	s_mov_b32 s2, 0x20000
	v_mul_f32_e32 v137, v96, v138
	v_cvt_pk_bf16_f32 v134, v136, v0
	v_add_co_u32_e32 v136, vcc, s2, v130
	v_cvt_pk_bf16_f32 v135, v137, v135
	s_nop 0
	v_addc_co_u32_e32 v137, vcc, 0, v131, vcc
	v_mul_f32_e32 v0, 0xbfb8aa3b, v86
	global_store_dwordx2 v[136:137], v[134:135], off
	v_exp_f32_e32 v134, v0
	v_mul_f32_e32 v0, 0xbfb8aa3b, v87
	v_exp_f32_e32 v135, v0
	s_nop 0
	v_pk_add_f32 v[134:135], v[134:135], 1.0 op_sel_hi:[1,0]
	s_nop 0
	v_rcp_f32_e32 v136, v135
	s_nop 0
	v_mul_f32_e32 v0, v87, v136
	v_rcp_f32_e32 v136, v134
	s_nop 0
	v_mul_f32_e32 v136, v86, v136
	v_mul_f32_e32 v134, 0xbfb8aa3b, v88
	v_mul_f32_e32 v135, 0xbfb8aa3b, v89
	v_exp_f32_e32 v134, v134
	v_exp_f32_e32 v135, v135
	s_nop 0
	v_pk_add_f32 v[134:135], v[134:135], 1.0 op_sel_hi:[1,0]
	s_nop 0
	v_rcp_f32_e32 v138, v135
	s_nop 0
	v_mul_f32_e32 v135, v89, v138
	v_rcp_f32_e32 v138, v134
	s_nop 0
	v_mul_f32_e32 v137, v88, v138
	v_cvt_pk_bf16_f32 v134, v136, v0
	v_cvt_pk_bf16_f32 v135, v137, v135
	v_mul_f32_e32 v0, 0xbfb8aa3b, v90
	global_store_dwordx2 v[132:133], v[134:135], off offset:32
	v_exp_f32_e32 v134, v0
	v_mul_f32_e32 v0, 0xbfb8aa3b, v91
	v_exp_f32_e32 v135, v0
	s_nop 0
	v_pk_add_f32 v[134:135], v[134:135], 1.0 op_sel_hi:[1,0]
	s_nop 0
	v_rcp_f32_e32 v136, v135
	s_nop 0
	v_mul_f32_e32 v0, v91, v136
	v_rcp_f32_e32 v136, v134
	s_nop 0
	v_mul_f32_e32 v136, v90, v136
	v_mul_f32_e32 v134, 0xbfb8aa3b, v92
	v_mul_f32_e32 v135, 0xbfb8aa3b, v93
	v_exp_f32_e32 v134, v134
	v_exp_f32_e32 v135, v135
	s_nop 0
	v_pk_add_f32 v[134:135], v[134:135], 1.0 op_sel_hi:[1,0]
	s_nop 0
	v_rcp_f32_e32 v138, v135
	s_nop 0
	v_mul_f32_e32 v135, v93, v138
	v_rcp_f32_e32 v138, v134
	s_nop 0
	v_mul_f32_e32 v137, v92, v138
	v_cvt_pk_bf16_f32 v134, v136, v0
	v_cvt_pk_bf16_f32 v135, v137, v135
	v_mul_f32_e32 v0, 0xbfb8aa3b, v82
	global_store_dwordx2 v[132:133], v[134:135], off offset:256
	v_exp_f32_e32 v134, v0
	v_mul_f32_e32 v0, 0xbfb8aa3b, v83
	v_exp_f32_e32 v135, v0
	s_nop 0
	v_pk_add_f32 v[134:135], v[134:135], 1.0 op_sel_hi:[1,0]
	s_nop 0
	v_rcp_f32_e32 v136, v135
	s_nop 0
	v_mul_f32_e32 v0, v83, v136
	v_rcp_f32_e32 v136, v134
	s_nop 0
	v_mul_f32_e32 v136, v82, v136
	v_mul_f32_e32 v134, 0xbfb8aa3b, v84
	v_mul_f32_e32 v135, 0xbfb8aa3b, v85
	v_exp_f32_e32 v134, v134
	v_exp_f32_e32 v135, v135
	s_nop 0
	v_pk_add_f32 v[134:135], v[134:135], 1.0 op_sel_hi:[1,0]
	s_nop 0
	v_rcp_f32_e32 v138, v135
	s_nop 0
	v_mul_f32_e32 v135, v85, v138
	v_rcp_f32_e32 v138, v134
	s_mov_b64 s[2:3], 0x30000
	v_mul_f32_e32 v137, v84, v138
	v_cvt_pk_bf16_f32 v134, v136, v0
	v_cvt_pk_bf16_f32 v135, v137, v135
	v_mul_f32_e32 v0, 0xbfb8aa3b, v78
	global_store_dwordx2 v[132:133], v[134:135], off offset:288
	v_exp_f32_e32 v134, v0
	v_mul_f32_e32 v0, 0xbfb8aa3b, v79
	v_exp_f32_e32 v135, v0
	v_lshl_add_u64 v[132:133], v[130:131], 0, s[2:3]
	v_pk_add_f32 v[134:135], v[134:135], 1.0 op_sel_hi:[1,0]
	s_nop 0
	v_rcp_f32_e32 v136, v135
	s_nop 0
	v_mul_f32_e32 v0, v79, v136
	v_rcp_f32_e32 v136, v134
	s_nop 0
	v_mul_f32_e32 v136, v78, v136
	v_mul_f32_e32 v134, 0xbfb8aa3b, v80
	v_mul_f32_e32 v135, 0xbfb8aa3b, v81
	v_exp_f32_e32 v134, v134
	v_exp_f32_e32 v135, v135
	s_nop 0
	v_pk_add_f32 v[134:135], v[134:135], 1.0 op_sel_hi:[1,0]
	s_nop 0
	v_rcp_f32_e32 v138, v135
	s_nop 0
	v_mul_f32_e32 v135, v81, v138
	v_rcp_f32_e32 v138, v134
	s_mov_b32 s2, 0x30000
	v_mul_f32_e32 v137, v80, v138
	v_cvt_pk_bf16_f32 v134, v136, v0
	v_add_co_u32_e32 v136, vcc, s2, v130
	v_cvt_pk_bf16_f32 v135, v137, v135
	s_nop 0
	v_addc_co_u32_e32 v137, vcc, 0, v131, vcc
	v_mul_f32_e32 v0, 0xbfb8aa3b, v70
	global_store_dwordx2 v[136:137], v[134:135], off
	v_exp_f32_e32 v134, v0
	v_mul_f32_e32 v0, 0xbfb8aa3b, v71
	v_exp_f32_e32 v135, v0
	s_nop 0
	v_pk_add_f32 v[134:135], v[134:135], 1.0 op_sel_hi:[1,0]
	s_nop 0
	v_rcp_f32_e32 v136, v135
	s_nop 0
	v_mul_f32_e32 v0, v71, v136
	v_rcp_f32_e32 v136, v134
	s_nop 0
	v_mul_f32_e32 v136, v70, v136
	v_mul_f32_e32 v134, 0xbfb8aa3b, v72
	v_mul_f32_e32 v135, 0xbfb8aa3b, v73
	v_exp_f32_e32 v134, v134
	v_exp_f32_e32 v135, v135
	s_nop 0
	v_pk_add_f32 v[134:135], v[134:135], 1.0 op_sel_hi:[1,0]
	s_nop 0
	v_rcp_f32_e32 v138, v135
	s_nop 0
	v_mul_f32_e32 v135, v73, v138
	v_rcp_f32_e32 v138, v134
	s_nop 0
	v_mul_f32_e32 v137, v72, v138
	v_cvt_pk_bf16_f32 v134, v136, v0
	v_cvt_pk_bf16_f32 v135, v137, v135
	v_mul_f32_e32 v0, 0xbfb8aa3b, v74
	global_store_dwordx2 v[132:133], v[134:135], off offset:32
	v_exp_f32_e32 v134, v0
	v_mul_f32_e32 v0, 0xbfb8aa3b, v75
	v_exp_f32_e32 v135, v0
	s_nop 0
	v_pk_add_f32 v[134:135], v[134:135], 1.0 op_sel_hi:[1,0]
	s_nop 0
	v_rcp_f32_e32 v136, v135
	s_nop 0
	v_mul_f32_e32 v0, v75, v136
	v_rcp_f32_e32 v136, v134
	s_nop 0
	v_mul_f32_e32 v136, v74, v136
	v_mul_f32_e32 v134, 0xbfb8aa3b, v76
	v_mul_f32_e32 v135, 0xbfb8aa3b, v77
	v_exp_f32_e32 v134, v134
	v_exp_f32_e32 v135, v135
	s_nop 0
	v_pk_add_f32 v[134:135], v[134:135], 1.0 op_sel_hi:[1,0]
	s_nop 0
	v_rcp_f32_e32 v138, v135
	s_nop 0
	v_mul_f32_e32 v135, v77, v138
	v_rcp_f32_e32 v138, v134
	s_nop 0
	v_mul_f32_e32 v137, v76, v138
	v_cvt_pk_bf16_f32 v134, v136, v0
	v_cvt_pk_bf16_f32 v135, v137, v135
	v_mul_f32_e32 v0, 0xbfb8aa3b, v66
	global_store_dwordx2 v[132:133], v[134:135], off offset:256
	v_exp_f32_e32 v134, v0
	v_mul_f32_e32 v0, 0xbfb8aa3b, v67
	v_exp_f32_e32 v135, v0
	s_nop 0
	v_pk_add_f32 v[134:135], v[134:135], 1.0 op_sel_hi:[1,0]
	s_nop 0
	v_rcp_f32_e32 v136, v135
	s_nop 0
	v_mul_f32_e32 v0, v67, v136
	v_rcp_f32_e32 v136, v134
	s_nop 0
	v_mul_f32_e32 v136, v66, v136
	v_mul_f32_e32 v134, 0xbfb8aa3b, v68
	v_mul_f32_e32 v135, 0xbfb8aa3b, v69
	v_exp_f32_e32 v134, v134
	v_exp_f32_e32 v135, v135
	s_nop 0
	v_pk_add_f32 v[134:135], v[134:135], 1.0 op_sel_hi:[1,0]
	s_nop 0
	v_rcp_f32_e32 v138, v135
	s_nop 0
	v_mul_f32_e32 v135, v69, v138
	v_rcp_f32_e32 v138, v134
	s_mov_b64 s[2:3], 0x80000
	v_mul_f32_e32 v137, v68, v138
	v_cvt_pk_bf16_f32 v134, v136, v0
	v_cvt_pk_bf16_f32 v135, v137, v135
	v_mul_f32_e32 v0, 0xbfb8aa3b, v62
	global_store_dwordx2 v[132:133], v[134:135], off offset:288
	v_exp_f32_e32 v134, v0
	v_mul_f32_e32 v0, 0xbfb8aa3b, v63
	v_exp_f32_e32 v135, v0
	v_lshl_add_u64 v[132:133], v[130:131], 0, s[2:3]
	v_pk_add_f32 v[134:135], v[134:135], 1.0 op_sel_hi:[1,0]
	s_nop 0
	v_rcp_f32_e32 v136, v135
	s_nop 0
	v_mul_f32_e32 v0, v63, v136
	v_rcp_f32_e32 v136, v134
	s_nop 0
	v_mul_f32_e32 v136, v62, v136
	v_mul_f32_e32 v134, 0xbfb8aa3b, v64
	v_mul_f32_e32 v135, 0xbfb8aa3b, v65
	v_exp_f32_e32 v134, v134
	v_exp_f32_e32 v135, v135
	s_nop 0
	v_pk_add_f32 v[134:135], v[134:135], 1.0 op_sel_hi:[1,0]
	s_nop 0
	v_rcp_f32_e32 v138, v135
	s_nop 0
	v_mul_f32_e32 v135, v65, v138
	v_rcp_f32_e32 v138, v134
	s_mov_b32 s2, 0x80000
	v_mul_f32_e32 v137, v64, v138
	v_cvt_pk_bf16_f32 v134, v136, v0
	v_add_co_u32_e32 v136, vcc, s2, v130
	v_cvt_pk_bf16_f32 v135, v137, v135
	s_nop 0
	v_addc_co_u32_e32 v137, vcc, 0, v131, vcc
	v_mul_f32_e32 v0, 0xbfb8aa3b, v54
	global_store_dwordx2 v[136:137], v[134:135], off
	v_exp_f32_e32 v134, v0
	v_mul_f32_e32 v0, 0xbfb8aa3b, v55
	v_exp_f32_e32 v135, v0
	s_nop 0
	v_pk_add_f32 v[134:135], v[134:135], 1.0 op_sel_hi:[1,0]
	s_nop 0
	v_rcp_f32_e32 v136, v135
	s_nop 0
	v_mul_f32_e32 v0, v55, v136
	v_rcp_f32_e32 v136, v134
	s_nop 0
	v_mul_f32_e32 v136, v54, v136
	v_mul_f32_e32 v134, 0xbfb8aa3b, v56
	v_mul_f32_e32 v135, 0xbfb8aa3b, v57
	v_exp_f32_e32 v134, v134
	v_exp_f32_e32 v135, v135
	s_nop 0
	v_pk_add_f32 v[134:135], v[134:135], 1.0 op_sel_hi:[1,0]
	s_nop 0
	v_rcp_f32_e32 v138, v135
	s_nop 0
	v_mul_f32_e32 v135, v57, v138
	v_rcp_f32_e32 v138, v134
	s_nop 0
	v_mul_f32_e32 v137, v56, v138
	v_cvt_pk_bf16_f32 v134, v136, v0
	v_cvt_pk_bf16_f32 v135, v137, v135
	v_mul_f32_e32 v0, 0xbfb8aa3b, v58
	global_store_dwordx2 v[132:133], v[134:135], off offset:32
	v_exp_f32_e32 v134, v0
	v_mul_f32_e32 v0, 0xbfb8aa3b, v59
	v_exp_f32_e32 v135, v0
	s_nop 0
	v_pk_add_f32 v[134:135], v[134:135], 1.0 op_sel_hi:[1,0]
	s_nop 0
	v_rcp_f32_e32 v136, v135
	s_nop 0
	v_mul_f32_e32 v0, v59, v136
	v_rcp_f32_e32 v136, v134
	s_nop 0
	v_mul_f32_e32 v136, v58, v136
	v_mul_f32_e32 v134, 0xbfb8aa3b, v60
	v_mul_f32_e32 v135, 0xbfb8aa3b, v61
	v_exp_f32_e32 v134, v134
	v_exp_f32_e32 v135, v135
	s_nop 0
	v_pk_add_f32 v[134:135], v[134:135], 1.0 op_sel_hi:[1,0]
	s_nop 0
	v_rcp_f32_e32 v138, v135
	s_nop 0
	v_mul_f32_e32 v135, v61, v138
	v_rcp_f32_e32 v138, v134
	s_nop 0
	v_mul_f32_e32 v137, v60, v138
	v_cvt_pk_bf16_f32 v134, v136, v0
	v_cvt_pk_bf16_f32 v135, v137, v135
	v_mul_f32_e32 v0, 0xbfb8aa3b, v50
	global_store_dwordx2 v[132:133], v[134:135], off offset:256
	v_exp_f32_e32 v134, v0
	v_mul_f32_e32 v0, 0xbfb8aa3b, v51
	v_exp_f32_e32 v135, v0
	s_nop 0
	v_pk_add_f32 v[134:135], v[134:135], 1.0 op_sel_hi:[1,0]
	s_nop 0
	v_rcp_f32_e32 v136, v135
	s_nop 0
	v_mul_f32_e32 v0, v51, v136
	v_rcp_f32_e32 v136, v134
	s_nop 0
	v_mul_f32_e32 v136, v50, v136
	v_mul_f32_e32 v134, 0xbfb8aa3b, v52
	v_mul_f32_e32 v135, 0xbfb8aa3b, v53
	v_exp_f32_e32 v134, v134
	v_exp_f32_e32 v135, v135
	s_nop 0
	v_pk_add_f32 v[134:135], v[134:135], 1.0 op_sel_hi:[1,0]
	s_nop 0
	v_rcp_f32_e32 v138, v135
	s_nop 0
	v_mul_f32_e32 v135, v53, v138
	v_rcp_f32_e32 v138, v134
	s_mov_b64 s[2:3], 0x90000
	v_mul_f32_e32 v137, v52, v138
	v_cvt_pk_bf16_f32 v134, v136, v0
	v_cvt_pk_bf16_f32 v135, v137, v135
	v_mul_f32_e32 v0, 0xbfb8aa3b, v46
	global_store_dwordx2 v[132:133], v[134:135], off offset:288
	v_exp_f32_e32 v134, v0
	v_mul_f32_e32 v0, 0xbfb8aa3b, v47
	v_exp_f32_e32 v135, v0
	v_lshl_add_u64 v[132:133], v[130:131], 0, s[2:3]
	v_pk_add_f32 v[134:135], v[134:135], 1.0 op_sel_hi:[1,0]
	s_nop 0
	v_rcp_f32_e32 v136, v135
	s_nop 0
	v_mul_f32_e32 v0, v47, v136
	v_rcp_f32_e32 v136, v134
	s_nop 0
	v_mul_f32_e32 v136, v46, v136
	v_mul_f32_e32 v134, 0xbfb8aa3b, v48
	v_mul_f32_e32 v135, 0xbfb8aa3b, v49
	v_exp_f32_e32 v134, v134
	v_exp_f32_e32 v135, v135
	s_nop 0
	v_pk_add_f32 v[134:135], v[134:135], 1.0 op_sel_hi:[1,0]
	s_nop 0
	v_rcp_f32_e32 v138, v135
	s_nop 0
	v_mul_f32_e32 v135, v49, v138
	v_rcp_f32_e32 v138, v134
	s_mov_b32 s2, 0x90000
	v_mul_f32_e32 v137, v48, v138
	v_cvt_pk_bf16_f32 v134, v136, v0
	v_add_co_u32_e32 v136, vcc, s2, v130
	v_cvt_pk_bf16_f32 v135, v137, v135
	s_nop 0
	v_addc_co_u32_e32 v137, vcc, 0, v131, vcc
	v_mul_f32_e32 v0, 0xbfb8aa3b, v38
	global_store_dwordx2 v[136:137], v[134:135], off
	v_exp_f32_e32 v134, v0
	v_mul_f32_e32 v0, 0xbfb8aa3b, v39
	v_exp_f32_e32 v135, v0
	s_nop 0
	v_pk_add_f32 v[134:135], v[134:135], 1.0 op_sel_hi:[1,0]
	s_nop 0
	v_rcp_f32_e32 v136, v135
	s_nop 0
	v_mul_f32_e32 v0, v39, v136
	v_rcp_f32_e32 v136, v134
	s_nop 0
	v_mul_f32_e32 v136, v38, v136
	v_mul_f32_e32 v134, 0xbfb8aa3b, v40
	v_mul_f32_e32 v135, 0xbfb8aa3b, v41
	v_exp_f32_e32 v134, v134
	v_exp_f32_e32 v135, v135
	s_nop 0
	v_pk_add_f32 v[134:135], v[134:135], 1.0 op_sel_hi:[1,0]
	s_nop 0
	v_rcp_f32_e32 v138, v135
	s_nop 0
	v_mul_f32_e32 v135, v41, v138
	v_rcp_f32_e32 v138, v134
	s_nop 0
	v_mul_f32_e32 v137, v40, v138
	v_cvt_pk_bf16_f32 v134, v136, v0
	v_cvt_pk_bf16_f32 v135, v137, v135
	v_mul_f32_e32 v0, 0xbfb8aa3b, v42
	global_store_dwordx2 v[132:133], v[134:135], off offset:32
	v_exp_f32_e32 v134, v0
	v_mul_f32_e32 v0, 0xbfb8aa3b, v43
	v_exp_f32_e32 v135, v0
	s_nop 0
	v_pk_add_f32 v[134:135], v[134:135], 1.0 op_sel_hi:[1,0]
	s_nop 0
	v_rcp_f32_e32 v136, v135
	s_nop 0
	v_mul_f32_e32 v0, v43, v136
	v_rcp_f32_e32 v136, v134
	s_nop 0
	v_mul_f32_e32 v136, v42, v136
	v_mul_f32_e32 v134, 0xbfb8aa3b, v44
	v_mul_f32_e32 v135, 0xbfb8aa3b, v45
	v_exp_f32_e32 v134, v134
	v_exp_f32_e32 v135, v135
	s_nop 0
	v_pk_add_f32 v[134:135], v[134:135], 1.0 op_sel_hi:[1,0]
	s_nop 0
	v_rcp_f32_e32 v138, v135
	s_nop 0
	v_mul_f32_e32 v135, v45, v138
	v_rcp_f32_e32 v138, v134
	s_nop 0
	v_mul_f32_e32 v137, v44, v138
	v_cvt_pk_bf16_f32 v134, v136, v0
	v_cvt_pk_bf16_f32 v135, v137, v135
	v_mul_f32_e32 v0, 0xbfb8aa3b, v34
	global_store_dwordx2 v[132:133], v[134:135], off offset:256
	v_exp_f32_e32 v134, v0
	v_mul_f32_e32 v0, 0xbfb8aa3b, v35
	v_exp_f32_e32 v135, v0
	s_nop 0
	v_pk_add_f32 v[134:135], v[134:135], 1.0 op_sel_hi:[1,0]
	s_nop 0
	v_rcp_f32_e32 v136, v135
	s_nop 0
	v_mul_f32_e32 v0, v35, v136
	v_rcp_f32_e32 v136, v134
	s_nop 0
	v_mul_f32_e32 v136, v34, v136
	v_mul_f32_e32 v134, 0xbfb8aa3b, v36
	v_mul_f32_e32 v135, 0xbfb8aa3b, v37
	v_exp_f32_e32 v134, v134
	v_exp_f32_e32 v135, v135
	s_nop 0
	v_pk_add_f32 v[134:135], v[134:135], 1.0 op_sel_hi:[1,0]
	s_nop 0
	v_rcp_f32_e32 v138, v135
	s_nop 0
	v_mul_f32_e32 v135, v37, v138
	v_rcp_f32_e32 v138, v134
	s_mov_b64 s[2:3], 0xa0000
	v_mul_f32_e32 v137, v36, v138
	v_cvt_pk_bf16_f32 v134, v136, v0
	v_cvt_pk_bf16_f32 v135, v137, v135
	v_mul_f32_e32 v0, 0xbfb8aa3b, v30
	global_store_dwordx2 v[132:133], v[134:135], off offset:288
	v_exp_f32_e32 v134, v0
	v_mul_f32_e32 v0, 0xbfb8aa3b, v31
	v_exp_f32_e32 v135, v0
	v_lshl_add_u64 v[132:133], v[130:131], 0, s[2:3]
	v_pk_add_f32 v[134:135], v[134:135], 1.0 op_sel_hi:[1,0]
	s_nop 0
	v_rcp_f32_e32 v136, v135
	s_nop 0
	v_mul_f32_e32 v0, v31, v136
	v_rcp_f32_e32 v136, v134
	s_nop 0
	v_mul_f32_e32 v136, v30, v136
	v_mul_f32_e32 v134, 0xbfb8aa3b, v32
	v_mul_f32_e32 v135, 0xbfb8aa3b, v33
	v_exp_f32_e32 v134, v134
	v_exp_f32_e32 v135, v135
	s_nop 0
	v_pk_add_f32 v[134:135], v[134:135], 1.0 op_sel_hi:[1,0]
	s_nop 0
	v_rcp_f32_e32 v138, v135
	s_nop 0
	v_mul_f32_e32 v135, v33, v138
	v_rcp_f32_e32 v138, v134
	s_mov_b32 s2, 0xa0000
	v_mul_f32_e32 v137, v32, v138
	v_cvt_pk_bf16_f32 v134, v136, v0
	v_add_co_u32_e32 v136, vcc, s2, v130
	v_cvt_pk_bf16_f32 v135, v137, v135
	s_nop 0
	v_addc_co_u32_e32 v137, vcc, 0, v131, vcc
	v_mul_f32_e32 v0, 0xbfb8aa3b, v22
	global_store_dwordx2 v[136:137], v[134:135], off
	v_exp_f32_e32 v134, v0
	v_mul_f32_e32 v0, 0xbfb8aa3b, v23
	v_exp_f32_e32 v135, v0
	s_nop 0
	v_pk_add_f32 v[134:135], v[134:135], 1.0 op_sel_hi:[1,0]
	s_nop 0
	v_rcp_f32_e32 v136, v135
	s_nop 0
	v_mul_f32_e32 v0, v23, v136
	v_rcp_f32_e32 v136, v134
	s_nop 0
	v_mul_f32_e32 v136, v22, v136
	v_mul_f32_e32 v134, 0xbfb8aa3b, v24
	v_mul_f32_e32 v135, 0xbfb8aa3b, v25
	v_exp_f32_e32 v134, v134
	v_exp_f32_e32 v135, v135
	s_nop 0
	v_pk_add_f32 v[134:135], v[134:135], 1.0 op_sel_hi:[1,0]
	s_nop 0
	v_rcp_f32_e32 v138, v135
	s_nop 0
	v_mul_f32_e32 v135, v25, v138
	v_rcp_f32_e32 v138, v134
	s_nop 0
	v_mul_f32_e32 v137, v24, v138
	v_cvt_pk_bf16_f32 v134, v136, v0
	v_cvt_pk_bf16_f32 v135, v137, v135
	v_mul_f32_e32 v0, 0xbfb8aa3b, v26
	global_store_dwordx2 v[132:133], v[134:135], off offset:32
	v_exp_f32_e32 v134, v0
	v_mul_f32_e32 v0, 0xbfb8aa3b, v27
	v_exp_f32_e32 v135, v0
	s_nop 0
	v_pk_add_f32 v[134:135], v[134:135], 1.0 op_sel_hi:[1,0]
	s_nop 0
	v_rcp_f32_e32 v136, v135
	s_nop 0
	v_mul_f32_e32 v0, v27, v136
	v_rcp_f32_e32 v136, v134
	s_nop 0
	v_mul_f32_e32 v136, v26, v136
	v_mul_f32_e32 v134, 0xbfb8aa3b, v28
	v_mul_f32_e32 v135, 0xbfb8aa3b, v29
	v_exp_f32_e32 v134, v134
	v_exp_f32_e32 v135, v135
	s_nop 0
	v_pk_add_f32 v[134:135], v[134:135], 1.0 op_sel_hi:[1,0]
	s_nop 0
	v_rcp_f32_e32 v138, v135
	s_nop 0
	v_mul_f32_e32 v135, v29, v138
	v_rcp_f32_e32 v138, v134
	s_nop 0
	v_mul_f32_e32 v137, v28, v138
	v_cvt_pk_bf16_f32 v134, v136, v0
	v_cvt_pk_bf16_f32 v135, v137, v135
	v_mul_f32_e32 v0, 0xbfb8aa3b, v18
	global_store_dwordx2 v[132:133], v[134:135], off offset:256
	v_exp_f32_e32 v134, v0
	v_mul_f32_e32 v0, 0xbfb8aa3b, v19
	v_exp_f32_e32 v135, v0
	s_nop 0
	v_pk_add_f32 v[134:135], v[134:135], 1.0 op_sel_hi:[1,0]
	s_nop 0
	v_rcp_f32_e32 v136, v135
	s_nop 0
	v_mul_f32_e32 v0, v19, v136
	v_rcp_f32_e32 v136, v134
	s_nop 0
	v_mul_f32_e32 v136, v18, v136
	v_mul_f32_e32 v134, 0xbfb8aa3b, v20
	v_mul_f32_e32 v135, 0xbfb8aa3b, v21
	v_exp_f32_e32 v134, v134
	v_exp_f32_e32 v135, v135
	s_nop 0
	v_pk_add_f32 v[134:135], v[134:135], 1.0 op_sel_hi:[1,0]
	s_nop 0
	v_rcp_f32_e32 v138, v135
	s_nop 0
	v_mul_f32_e32 v135, v21, v138
	v_rcp_f32_e32 v138, v134
	s_mov_b64 s[2:3], 0xb0000
	v_mul_f32_e32 v137, v20, v138
	v_cvt_pk_bf16_f32 v134, v136, v0
	v_cvt_pk_bf16_f32 v135, v137, v135
	v_mul_f32_e32 v0, 0xbfb8aa3b, v14
	global_store_dwordx2 v[132:133], v[134:135], off offset:288
	v_exp_f32_e32 v134, v0
	v_mul_f32_e32 v0, 0xbfb8aa3b, v15
	v_exp_f32_e32 v135, v0
	v_lshl_add_u64 v[132:133], v[130:131], 0, s[2:3]
	v_pk_add_f32 v[134:135], v[134:135], 1.0 op_sel_hi:[1,0]
	s_nop 0
	v_rcp_f32_e32 v136, v135
	s_nop 0
	v_mul_f32_e32 v0, v15, v136
	v_rcp_f32_e32 v136, v134
	s_nop 0
	v_mul_f32_e32 v136, v14, v136
	v_mul_f32_e32 v134, 0xbfb8aa3b, v16
	v_mul_f32_e32 v135, 0xbfb8aa3b, v17
	v_exp_f32_e32 v134, v134
	v_exp_f32_e32 v135, v135
	s_nop 0
	v_pk_add_f32 v[134:135], v[134:135], 1.0 op_sel_hi:[1,0]
	s_nop 0
	v_rcp_f32_e32 v138, v135
	s_nop 0
	v_mul_f32_e32 v135, v17, v138
	v_rcp_f32_e32 v138, v134
	s_mov_b32 s2, 0xb0000
	v_mul_f32_e32 v137, v16, v138
	v_add_co_u32_e32 v130, vcc, s2, v130
	v_cvt_pk_bf16_f32 v134, v136, v0
	v_cvt_pk_bf16_f32 v135, v137, v135
	v_addc_co_u32_e32 v131, vcc, 0, v131, vcc
	v_mul_f32_e32 v0, 0xbfb8aa3b, v6
	global_store_dwordx2 v[130:131], v[134:135], off
	v_exp_f32_e32 v130, v0
	v_mul_f32_e32 v0, 0xbfb8aa3b, v7
	v_exp_f32_e32 v131, v0
	s_nop 0
	v_pk_add_f32 v[130:131], v[130:131], 1.0 op_sel_hi:[1,0]
	s_nop 0
	v_rcp_f32_e32 v134, v131
	s_nop 0
	v_mul_f32_e32 v0, v7, v134
	v_rcp_f32_e32 v134, v130
	s_nop 0
	v_mul_f32_e32 v134, v6, v134
	v_mul_f32_e32 v130, 0xbfb8aa3b, v8
	v_mul_f32_e32 v131, 0xbfb8aa3b, v9
	v_exp_f32_e32 v130, v130
	v_exp_f32_e32 v131, v131
	s_nop 0
	v_pk_add_f32 v[130:131], v[130:131], 1.0 op_sel_hi:[1,0]
	s_nop 0
	v_rcp_f32_e32 v136, v131
	s_nop 0
	v_mul_f32_e32 v131, v9, v136
	v_rcp_f32_e32 v136, v130
	s_nop 0
	v_mul_f32_e32 v135, v8, v136
	v_cvt_pk_bf16_f32 v130, v134, v0
	v_cvt_pk_bf16_f32 v131, v135, v131
	v_mul_f32_e32 v0, 0xbfb8aa3b, v10
	global_store_dwordx2 v[132:133], v[130:131], off offset:32
	v_exp_f32_e32 v130, v0
	v_mul_f32_e32 v0, 0xbfb8aa3b, v11
	v_exp_f32_e32 v131, v0
	s_nop 0
	v_pk_add_f32 v[130:131], v[130:131], 1.0 op_sel_hi:[1,0]
	s_nop 0
	v_rcp_f32_e32 v134, v131
	s_nop 0
	v_mul_f32_e32 v0, v11, v134
	v_rcp_f32_e32 v134, v130
	s_nop 0
	v_mul_f32_e32 v134, v10, v134
	v_mul_f32_e32 v130, 0xbfb8aa3b, v12
	v_mul_f32_e32 v131, 0xbfb8aa3b, v13
	v_exp_f32_e32 v130, v130
	v_exp_f32_e32 v131, v131
	s_nop 0
	v_pk_add_f32 v[130:131], v[130:131], 1.0 op_sel_hi:[1,0]
	s_nop 0
	v_rcp_f32_e32 v136, v131
	s_nop 0
	v_mul_f32_e32 v131, v13, v136
	v_rcp_f32_e32 v136, v130
	s_nop 0
	v_mul_f32_e32 v135, v12, v136
	v_cvt_pk_bf16_f32 v130, v134, v0
	v_cvt_pk_bf16_f32 v131, v135, v131
	v_mul_f32_e32 v0, 0xbfb8aa3b, v2
	global_store_dwordx2 v[132:133], v[130:131], off offset:256
	v_exp_f32_e32 v130, v0
	v_mul_f32_e32 v0, 0xbfb8aa3b, v3
	v_exp_f32_e32 v131, v0
	s_nop 0
	v_pk_add_f32 v[130:131], v[130:131], 1.0 op_sel_hi:[1,0]
	s_nop 0
	v_rcp_f32_e32 v134, v131
	s_nop 0
	v_mul_f32_e32 v0, v3, v134
	v_rcp_f32_e32 v134, v130
	s_nop 0
	v_mul_f32_e32 v134, v2, v134
	v_mul_f32_e32 v130, 0xbfb8aa3b, v4
	v_mul_f32_e32 v131, 0xbfb8aa3b, v5
	v_exp_f32_e32 v130, v130
	v_exp_f32_e32 v131, v131
	s_nop 0
	v_pk_add_f32 v[130:131], v[130:131], 1.0 op_sel_hi:[1,0]
	s_nop 0
	v_rcp_f32_e32 v136, v131
	s_nop 0
	v_mul_f32_e32 v131, v5, v136
	v_rcp_f32_e32 v136, v130
	s_nop 0
	v_mul_f32_e32 v135, v4, v136
	v_cvt_pk_bf16_f32 v130, v134, v0
	v_cvt_pk_bf16_f32 v131, v135, v131
	global_store_dwordx2 v[132:133], v[130:131], off offset:288
